# up epilogue: row pairs packed via permlane16_swap, 8 dwordx4 stores instead of 16 dwordx2
# speedup vs baseline: 1.0011x; 1.0011x over previous
.LBB0_104:
	s_add_u32 s2, s34, 0xfffc2080
	s_addc_u32 s3, s35, -1
	s_add_i32 s12, 0, 0x10000
	v_add_u32_e32 v110, s12, v179
	ds_read_b128 v[98:101], v110
	ds_read_b128 v[102:105], v110 offset:1024
	ds_read_b128 v[106:109], v110 offset:2048
	ds_read_b128 v[110:113], v110 offset:3072
	s_cmp_eq_u32 s53, 12
	s_cselect_b32 s49, s97, s3
	s_cselect_b32 s48, s96, s2
	s_cselect_b32 s3, s1, s52
	s_cselect_b32 s2, s23, s51
	v_lshl_add_u64 v[174:175], s[34:35], 0, v[170:171]
	s_add_i32 m0, s85, 0xc000
	ds_read_b128 v[114:117], v184
	ds_read_b128 v[118:121], v184 offset:1024
	ds_read_b128 v[122:125], v184 offset:2048
	ds_read_b128 v[126:129], v184 offset:3072
	ds_read_b128 v[186:189], v184 offset:4096
	ds_read_b128 v[190:193], v184 offset:5120
	ds_read_b128 v[194:197], v184 offset:6144
	ds_read_b128 v[198:201], v184 offset:7168
	global_load_lds_dwordx4 v[174:175], off
	v_lshl_add_u64 v[174:175], s[34:35], 0, v[172:173]
	s_add_i32 m0, s85, 0xe000
	s_nop 0
	global_load_lds_dwordx4 v[174:175], off
	s_waitcnt lgkmcnt(8)
	s_barrier
	s_waitcnt lgkmcnt(0)
	s_waitcnt lgkmcnt(0)
	v_mfma_f32_16x16x32_bf16 v[158:161], v[98:101], v[114:117], v[158:161]
	v_mfma_f32_16x16x32_bf16 v[154:157], v[106:109], v[114:117], v[154:157]
	v_mfma_f32_16x16x32_bf16 v[150:153], v[98:101], v[122:125], v[150:153]
	v_mfma_f32_16x16x32_bf16 v[146:149], v[106:109], v[122:125], v[146:149]
	v_mfma_f32_16x16x32_bf16 v[142:145], v[98:101], v[186:189], v[142:145]
	v_mfma_f32_16x16x32_bf16 v[138:141], v[106:109], v[186:189], v[138:141]
	v_mfma_f32_16x16x32_bf16 v[134:137], v[98:101], v[194:197], v[134:137]
	v_mfma_f32_16x16x32_bf16 v[130:133], v[106:109], v[194:197], v[130:133]
	v_mfma_f32_16x16x32_bf16 v[158:161], v[102:105], v[118:121], v[158:161]
	v_mfma_f32_16x16x32_bf16 v[154:157], v[110:113], v[118:121], v[154:157]
	v_mfma_f32_16x16x32_bf16 v[150:153], v[102:105], v[126:129], v[150:153]
	v_mfma_f32_16x16x32_bf16 v[146:149], v[110:113], v[126:129], v[146:149]
	v_mfma_f32_16x16x32_bf16 v[142:145], v[102:105], v[190:193], v[142:145]
	v_mfma_f32_16x16x32_bf16 v[138:141], v[110:113], v[190:193], v[138:141]
	v_mfma_f32_16x16x32_bf16 v[134:137], v[102:105], v[198:201], v[134:137]
	v_mfma_f32_16x16x32_bf16 v[130:133], v[110:113], v[198:201], v[130:133]
	s_barrier
	s_add_i32 s54, 0, 0x14000
	v_add_u32_e32 v174, s54, v179
	s_add_i32 s12, s12, s78
	ds_read_b128 v[226:229], v174
	ds_read_b128 v[230:233], v174 offset:1024
	ds_read_b128 v[234:237], v174 offset:2048
	ds_read_b128 v[242:245], v174 offset:3072
	v_lshl_add_u64 v[174:175], s[2:3], 0, v[0:1]
	s_mov_b32 m0, s12
	v_lshl_add_u64 v[246:247], s[2:3], 0, v[166:167]
	global_load_lds_dwordx4 v[174:175], off
	s_add_i32 m0, s12, 0x2000
	s_nop 0
	global_load_lds_dwordx4 v[246:247], off
	s_barrier
	s_waitcnt lgkmcnt(0)
	s_waitcnt lgkmcnt(0)
	v_mfma_f32_16x16x32_bf16 v[62:65], v[226:229], v[114:117], v[62:65]
	v_mfma_f32_16x16x32_bf16 v[58:61], v[234:237], v[114:117], v[58:61]
	v_mfma_f32_16x16x32_bf16 v[54:57], v[226:229], v[122:125], v[54:57]
	v_mfma_f32_16x16x32_bf16 v[50:53], v[234:237], v[122:125], v[50:53]
	v_mfma_f32_16x16x32_bf16 v[46:49], v[226:229], v[186:189], v[46:49]
	v_mfma_f32_16x16x32_bf16 v[42:45], v[234:237], v[186:189], v[42:45]
	v_mfma_f32_16x16x32_bf16 v[38:41], v[226:229], v[194:197], v[38:41]
	v_mfma_f32_16x16x32_bf16 v[34:37], v[234:237], v[194:197], v[34:37]
	v_mfma_f32_16x16x32_bf16 v[62:65], v[230:233], v[118:121], v[62:65]
	v_mfma_f32_16x16x32_bf16 v[58:61], v[242:245], v[118:121], v[58:61]
	v_mfma_f32_16x16x32_bf16 v[54:57], v[230:233], v[126:129], v[54:57]
	v_mfma_f32_16x16x32_bf16 v[50:53], v[242:245], v[126:129], v[50:53]
	v_mfma_f32_16x16x32_bf16 v[46:49], v[230:233], v[190:193], v[46:49]
	v_mfma_f32_16x16x32_bf16 v[42:45], v[242:245], v[190:193], v[42:45]
	v_mfma_f32_16x16x32_bf16 v[38:41], v[230:233], v[198:201], v[38:41]
	v_mfma_f32_16x16x32_bf16 v[34:37], v[242:245], v[198:201], v[34:37]
	s_mov_b32 m0, s85
	v_lshl_add_u64 v[248:249], s[48:49], 0, v[162:163]
	s_barrier
	ds_read_b128 v[114:117], v184 offset:16384
	ds_read_b128 v[118:121], v184 offset:17408
	ds_read_b128 v[122:125], v184 offset:18432
	ds_read_b128 v[126:129], v184 offset:19456
	ds_read_b128 v[186:189], v184 offset:20480
	ds_read_b128 v[190:193], v184 offset:21504
	ds_read_b128 v[194:197], v184 offset:22528
	ds_read_b128 v[198:201], v184 offset:23552
	global_load_lds_dwordx4 v[248:249], off
	v_lshl_add_u64 v[250:251], s[48:49], 0, v[164:165]
	s_mov_b32 m0, s82
	s_nop 0
	global_load_lds_dwordx4 v[250:251], off
	s_barrier
	s_waitcnt lgkmcnt(0)
	s_waitcnt lgkmcnt(0)
	v_mfma_f32_16x16x32_bf16 v[94:97], v[98:101], v[114:117], v[94:97]
	v_mfma_f32_16x16x32_bf16 v[90:93], v[106:109], v[114:117], v[90:93]
	v_mfma_f32_16x16x32_bf16 v[86:89], v[98:101], v[122:125], v[86:89]
	v_mfma_f32_16x16x32_bf16 v[82:85], v[106:109], v[122:125], v[82:85]
	v_mfma_f32_16x16x32_bf16 v[78:81], v[98:101], v[186:189], v[78:81]
	v_mfma_f32_16x16x32_bf16 v[74:77], v[106:109], v[186:189], v[74:77]
	v_mfma_f32_16x16x32_bf16 v[70:73], v[98:101], v[194:197], v[70:73]
	v_mfma_f32_16x16x32_bf16 v[66:69], v[106:109], v[194:197], v[66:69]
	v_mfma_f32_16x16x32_bf16 v[94:97], v[102:105], v[118:121], v[94:97]
	v_mfma_f32_16x16x32_bf16 v[90:93], v[110:113], v[118:121], v[90:93]
	v_mfma_f32_16x16x32_bf16 v[86:89], v[102:105], v[126:129], v[86:89]
	v_mfma_f32_16x16x32_bf16 v[82:85], v[110:113], v[126:129], v[82:85]
	v_mfma_f32_16x16x32_bf16 v[78:81], v[102:105], v[190:193], v[78:81]
	v_mfma_f32_16x16x32_bf16 v[74:77], v[110:113], v[190:193], v[74:77]
	v_mfma_f32_16x16x32_bf16 v[70:73], v[102:105], v[198:201], v[70:73]
	v_mfma_f32_16x16x32_bf16 v[66:69], v[110:113], v[198:201], v[66:69]
	s_barrier
	s_add_u32 s12, s2, 0x40000
	s_addc_u32 s13, s3, 0
	s_add_i32 s54, s54, s78
	v_lshl_add_u64 v[98:99], s[12:13], 0, v[0:1]
	s_mov_b32 m0, s54
	s_nop 0
	global_load_lds_dwordx4 v[98:99], off
	v_lshl_add_u64 v[98:99], s[12:13], 0, v[166:167]
	s_add_i32 m0, s54, 0x2000
	s_nop 0
	global_load_lds_dwordx4 v[98:99], off
	s_waitcnt vmcnt(6)
	s_barrier
	v_mfma_f32_16x16x32_bf16 v[30:33], v[226:229], v[114:117], v[30:33]
	v_mfma_f32_16x16x32_bf16 v[26:29], v[234:237], v[114:117], v[26:29]
	v_mfma_f32_16x16x32_bf16 v[22:25], v[226:229], v[122:125], v[22:25]
	v_mfma_f32_16x16x32_bf16 v[18:21], v[234:237], v[122:125], v[18:21]
	v_mfma_f32_16x16x32_bf16 v[14:17], v[226:229], v[186:189], v[14:17]
	v_mfma_f32_16x16x32_bf16 v[10:13], v[234:237], v[186:189], v[10:13]
	v_mfma_f32_16x16x32_bf16 v[6:9], v[226:229], v[194:197], v[6:9]
	v_mfma_f32_16x16x32_bf16 v[2:5], v[234:237], v[194:197], v[2:5]
	v_mfma_f32_16x16x32_bf16 v[30:33], v[230:233], v[118:121], v[30:33]
	v_mfma_f32_16x16x32_bf16 v[26:29], v[242:245], v[118:121], v[26:29]
	v_mfma_f32_16x16x32_bf16 v[22:25], v[230:233], v[126:129], v[22:25]
	v_mfma_f32_16x16x32_bf16 v[18:21], v[242:245], v[126:129], v[18:21]
	v_mfma_f32_16x16x32_bf16 v[14:17], v[230:233], v[190:193], v[14:17]
	v_mfma_f32_16x16x32_bf16 v[10:13], v[242:245], v[190:193], v[10:13]
	v_mfma_f32_16x16x32_bf16 v[6:9], v[230:233], v[198:201], v[6:9]
	v_mfma_f32_16x16x32_bf16 v[2:5], v[242:245], v[198:201], v[2:5]
	s_add_i32 s54, 0, 0x18000
	v_add_u32_e32 v110, s54, v179
	s_barrier
	ds_read_b128 v[98:101], v110
	ds_read_b128 v[102:105], v110 offset:1024
	ds_read_b128 v[106:109], v110 offset:2048
	ds_read_b128 v[110:113], v110 offset:3072
	s_add_u32 s12, s48, 0x3e000
	s_addc_u32 s13, s49, 0
	s_mov_b32 m0, s89
	v_lshl_add_u64 v[226:227], s[12:13], 0, v[162:163]
	ds_read_b128 v[114:117], v184 offset:32768
	ds_read_b128 v[118:121], v184 offset:33792
	ds_read_b128 v[122:125], v184 offset:34816
	ds_read_b128 v[126:129], v184 offset:35840
	ds_read_b128 v[186:189], v184 offset:36864
	ds_read_b128 v[190:193], v184 offset:37888
	ds_read_b128 v[194:197], v184 offset:38912
	ds_read_b128 v[198:201], v184 offset:39936
	global_load_lds_dwordx4 v[226:227], off
	v_lshl_add_u64 v[226:227], s[12:13], 0, v[164:165]
	s_mov_b32 m0, s91
	s_nop 0
	global_load_lds_dwordx4 v[226:227], off
	s_waitcnt lgkmcnt(8)
	s_barrier
	s_waitcnt lgkmcnt(0)
	s_waitcnt lgkmcnt(0)
	v_mfma_f32_16x16x32_bf16 v[158:161], v[98:101], v[114:117], v[158:161]
	v_mfma_f32_16x16x32_bf16 v[154:157], v[106:109], v[114:117], v[154:157]
	v_mfma_f32_16x16x32_bf16 v[150:153], v[98:101], v[122:125], v[150:153]
	v_mfma_f32_16x16x32_bf16 v[146:149], v[106:109], v[122:125], v[146:149]
	v_mfma_f32_16x16x32_bf16 v[142:145], v[98:101], v[186:189], v[142:145]
	v_mfma_f32_16x16x32_bf16 v[138:141], v[106:109], v[186:189], v[138:141]
	v_mfma_f32_16x16x32_bf16 v[134:137], v[98:101], v[194:197], v[134:137]
	v_mfma_f32_16x16x32_bf16 v[130:133], v[106:109], v[194:197], v[130:133]
	v_mfma_f32_16x16x32_bf16 v[158:161], v[102:105], v[118:121], v[158:161]
	v_mfma_f32_16x16x32_bf16 v[154:157], v[110:113], v[118:121], v[154:157]
	v_mfma_f32_16x16x32_bf16 v[150:153], v[102:105], v[126:129], v[150:153]
	v_mfma_f32_16x16x32_bf16 v[146:149], v[110:113], v[126:129], v[146:149]
	v_mfma_f32_16x16x32_bf16 v[142:145], v[102:105], v[190:193], v[142:145]
	v_mfma_f32_16x16x32_bf16 v[138:141], v[110:113], v[190:193], v[138:141]
	v_mfma_f32_16x16x32_bf16 v[134:137], v[102:105], v[198:201], v[134:137]
	v_mfma_f32_16x16x32_bf16 v[130:133], v[110:113], v[198:201], v[130:133]
	s_barrier
	s_add_i32 s12, 0, 0x1c000
	s_add_i32 s13, s54, s78
	v_add_u32_e32 v242, s12, v179
	v_lshl_add_u64 v[174:175], v[174:175], 0, s[20:21]
	s_mov_b32 m0, s13
	ds_read_b128 v[226:229], v242
	ds_read_b128 v[230:233], v242 offset:1024
	ds_read_b128 v[234:237], v242 offset:2048
	ds_read_b128 v[242:245], v242 offset:3072
	global_load_lds_dwordx4 v[174:175], off
	v_lshl_add_u64 v[174:175], v[246:247], 0, s[20:21]
	s_add_i32 m0, s13, 0x2000
	s_nop 0
	global_load_lds_dwordx4 v[174:175], off
	s_barrier
	s_waitcnt lgkmcnt(0)
	s_waitcnt lgkmcnt(0)
	v_mfma_f32_16x16x32_bf16 v[62:65], v[226:229], v[114:117], v[62:65]
	v_mfma_f32_16x16x32_bf16 v[58:61], v[234:237], v[114:117], v[58:61]
	v_mfma_f32_16x16x32_bf16 v[54:57], v[226:229], v[122:125], v[54:57]
	v_mfma_f32_16x16x32_bf16 v[50:53], v[234:237], v[122:125], v[50:53]
	v_mfma_f32_16x16x32_bf16 v[46:49], v[226:229], v[186:189], v[46:49]
	v_mfma_f32_16x16x32_bf16 v[42:45], v[234:237], v[186:189], v[42:45]
	v_mfma_f32_16x16x32_bf16 v[38:41], v[226:229], v[194:197], v[38:41]
	v_mfma_f32_16x16x32_bf16 v[34:37], v[234:237], v[194:197], v[34:37]
	v_mfma_f32_16x16x32_bf16 v[62:65], v[230:233], v[118:121], v[62:65]
	v_mfma_f32_16x16x32_bf16 v[58:61], v[242:245], v[118:121], v[58:61]
	v_mfma_f32_16x16x32_bf16 v[54:57], v[230:233], v[126:129], v[54:57]
	v_mfma_f32_16x16x32_bf16 v[50:53], v[242:245], v[126:129], v[50:53]
	v_mfma_f32_16x16x32_bf16 v[46:49], v[230:233], v[190:193], v[46:49]
	v_mfma_f32_16x16x32_bf16 v[42:45], v[242:245], v[190:193], v[42:45]
	v_mfma_f32_16x16x32_bf16 v[38:41], v[230:233], v[198:201], v[38:41]
	v_mfma_f32_16x16x32_bf16 v[34:37], v[242:245], v[198:201], v[34:37]
	s_mov_b32 m0, s79
	v_lshl_add_u64 v[174:175], v[248:249], 0, s[20:21]
	s_barrier
	ds_read_b128 v[114:117], v184 offset:49152
	ds_read_b128 v[118:121], v184 offset:50176
	ds_read_b128 v[122:125], v184 offset:51200
	ds_read_b128 v[126:129], v184 offset:52224
	ds_read_b128 v[186:189], v184 offset:53248
	ds_read_b128 v[190:193], v184 offset:54272
	ds_read_b128 v[194:197], v184 offset:55296
	ds_read_b128 v[198:201], v184 offset:56320
	global_load_lds_dwordx4 v[174:175], off
	v_lshl_add_u64 v[174:175], v[250:251], 0, s[20:21]
	s_mov_b32 m0, s87
	s_nop 0
	global_load_lds_dwordx4 v[174:175], off
	s_barrier
	s_waitcnt lgkmcnt(0)
	s_waitcnt lgkmcnt(0)
	v_mfma_f32_16x16x32_bf16 v[94:97], v[98:101], v[114:117], v[94:97]
	v_mfma_f32_16x16x32_bf16 v[90:93], v[106:109], v[114:117], v[90:93]
	v_mfma_f32_16x16x32_bf16 v[86:89], v[98:101], v[122:125], v[86:89]
	v_mfma_f32_16x16x32_bf16 v[82:85], v[106:109], v[122:125], v[82:85]
	v_mfma_f32_16x16x32_bf16 v[78:81], v[98:101], v[186:189], v[78:81]
	v_mfma_f32_16x16x32_bf16 v[74:77], v[106:109], v[186:189], v[74:77]
	v_mfma_f32_16x16x32_bf16 v[70:73], v[98:101], v[194:197], v[70:73]
	v_mfma_f32_16x16x32_bf16 v[66:69], v[106:109], v[194:197], v[66:69]
	v_mfma_f32_16x16x32_bf16 v[94:97], v[102:105], v[118:121], v[94:97]
	v_mfma_f32_16x16x32_bf16 v[90:93], v[110:113], v[118:121], v[90:93]
	v_mfma_f32_16x16x32_bf16 v[86:89], v[102:105], v[126:129], v[86:89]
	v_mfma_f32_16x16x32_bf16 v[82:85], v[110:113], v[126:129], v[82:85]
	v_mfma_f32_16x16x32_bf16 v[78:81], v[102:105], v[190:193], v[78:81]
	v_mfma_f32_16x16x32_bf16 v[74:77], v[110:113], v[190:193], v[74:77]
	v_mfma_f32_16x16x32_bf16 v[70:73], v[102:105], v[198:201], v[70:73]
	v_mfma_f32_16x16x32_bf16 v[66:69], v[110:113], v[198:201], v[66:69]
	s_barrier
	s_add_u32 s2, s2, 0x40080
	s_addc_u32 s3, s3, 0
	s_add_i32 s12, s12, s78
	v_lshl_add_u64 v[98:99], s[2:3], 0, v[0:1]
	s_mov_b32 m0, s12
	s_nop 0
	global_load_lds_dwordx4 v[98:99], off
	v_lshl_add_u64 v[98:99], s[2:3], 0, v[166:167]
	s_add_i32 m0, s12, 0x2000
	s_nop 0
	global_load_lds_dwordx4 v[98:99], off
	s_waitcnt vmcnt(6)
	s_barrier
	v_mfma_f32_16x16x32_bf16 v[30:33], v[226:229], v[114:117], v[30:33]
	v_mfma_f32_16x16x32_bf16 v[26:29], v[234:237], v[114:117], v[26:29]
	v_mfma_f32_16x16x32_bf16 v[22:25], v[226:229], v[122:125], v[22:25]
	v_mfma_f32_16x16x32_bf16 v[18:21], v[234:237], v[122:125], v[18:21]
	v_mfma_f32_16x16x32_bf16 v[14:17], v[226:229], v[186:189], v[14:17]
	v_mfma_f32_16x16x32_bf16 v[10:13], v[234:237], v[186:189], v[10:13]
	v_mfma_f32_16x16x32_bf16 v[6:9], v[226:229], v[194:197], v[6:9]
	v_mfma_f32_16x16x32_bf16 v[2:5], v[234:237], v[194:197], v[2:5]
	v_mfma_f32_16x16x32_bf16 v[30:33], v[230:233], v[118:121], v[30:33]
	v_mfma_f32_16x16x32_bf16 v[26:29], v[242:245], v[118:121], v[26:29]
	v_mfma_f32_16x16x32_bf16 v[22:25], v[230:233], v[126:129], v[22:25]
	v_mfma_f32_16x16x32_bf16 v[18:21], v[242:245], v[126:129], v[18:21]
	v_mfma_f32_16x16x32_bf16 v[14:17], v[230:233], v[190:193], v[14:17]
	v_mfma_f32_16x16x32_bf16 v[10:13], v[242:245], v[190:193], v[10:13]
	v_mfma_f32_16x16x32_bf16 v[6:9], v[230:233], v[198:201], v[6:9]
	v_mfma_f32_16x16x32_bf16 v[2:5], v[242:245], v[198:201], v[2:5]
	s_add_i32 s53, s53, 2
	s_add_u32 s34, s34, 0x100
	s_addc_u32 s35, s35, 0
	s_add_u32 s51, s51, 0x100
	s_addc_u32 s52, s52, 0
	s_cmp_gt_u32 s53, 13
	s_barrier
	s_cbranch_scc0 .LBB0_104
	s_add_i32 s1, s50, 0xffffffbd
	s_cmpk_gt_i32 s50, 0x42
	s_cselect_b32 s1, s1, s50
	s_mul_i32 s23, s1, 0xf8
	s_cselect_b32 s2, 0x4000, 0
	s_cselect_b32 s3, 0x100, s37
	s_add_i32 s23, s23, s84
	v_add_u32_e32 v188, s88, v178
	ds_read_b128 v[126:129], v188
	ds_read_b128 v[122:125], v188 offset:128
	ds_read_b128 v[114:117], v188 offset:256
	ds_read_b128 v[118:121], v188 offset:384
	ds_read_b128 v[110:113], v188 offset:512
	ds_read_b128 v[106:109], v188 offset:640
	ds_read_b128 v[98:101], v188 offset:768
	ds_read_b128 v[102:105], v188 offset:896
	v_readlane_b32 s12, v252, 28
	v_readlane_b32 s13, v252, 29
	v_bfe_u32 v231, v202, 5, 1
	v_and_b32_e32 v174, 48, v180
	v_lshl_or_b32 v174, v231, 3, v174
	v_lshl_or_b32 v174, s0, 7, v174
	v_bfe_u32 v230, v202, 4, 1
	v_lshl_add_u32 v186, v177, 2, s23
	v_cmp_eq_u32_e32 vcc, 1, v230
	s_or_b64 s[52:53], s[42:43], vcc
	v_cmp_eq_u32_e32 vcc, 0, v230
	s_or_b64 s[54:55], s[44:45], vcc
	v_add_u32_e32 v186, v186, v230
	v_add_u32_e32 v187, s2, v186
	v_mul_u32_u24_e32 v187, 0x1600, v187
	v_lshl_add_u32 v187, v174, 1, v187
	s_waitcnt lgkmcnt(0)
	v_fma_f32 v190, v158, v122, v118
	v_fma_f32 v191, v159, v123, v119
	v_fma_f32 v192, v160, v124, v120
	v_fma_f32 v193, v161, v125, v121
	v_fma_f32 v194, v154, v106, v102
	v_fma_f32 v195, v155, v107, v103
	v_fma_f32 v196, v156, v108, v104
	v_fma_f32 v197, v157, v109, v105
	v_add_u32_e32 v230, 0, v186
	v_fmac_f32_dpp v190, v134, v126 row_ror:1 row_mask:0xf bank_mask:0xf
	v_fmac_f32_dpp v191, v135, v127 row_ror:1 row_mask:0xf bank_mask:0xf
	v_fmac_f32_dpp v192, v136, v128 row_ror:1 row_mask:0xf bank_mask:0xf
	v_fmac_f32_dpp v193, v137, v129 row_ror:1 row_mask:0xf bank_mask:0xf
	v_fmac_f32_dpp v194, v130, v110 row_ror:1 row_mask:0xf bank_mask:0xf
	v_fmac_f32_dpp v195, v131, v111 row_ror:1 row_mask:0xf bank_mask:0xf
	v_fmac_f32_dpp v196, v132, v112 row_ror:1 row_mask:0xf bank_mask:0xf
	v_fmac_f32_dpp v197, v133, v113 row_ror:1 row_mask:0xf bank_mask:0xf
	v_fmac_f32_e32 v190, v150, v114
	v_fmac_f32_e32 v191, v151, v115
	v_fmac_f32_e32 v192, v152, v116
	v_fmac_f32_e32 v193, v153, v117
	v_fmac_f32_e32 v194, v146, v98
	v_fmac_f32_e32 v195, v147, v99
	v_fmac_f32_e32 v196, v148, v100
	v_fmac_f32_e32 v197, v149, v101
	v_mul_f32_e32 v198, 0xbfb8aa3b, v190
	v_mul_f32_e32 v199, 0xbfb8aa3b, v191
	v_mul_f32_e32 v200, 0xbfb8aa3b, v192
	v_mul_f32_e32 v201, 0xbfb8aa3b, v193
	v_exp_f32_e32 v198, v198
	v_exp_f32_e32 v199, v199
	v_exp_f32_e32 v200, v200
	v_exp_f32_e32 v201, v201
	v_add_f32_e32 v198, 1.0, v198
	v_add_f32_e32 v199, 1.0, v199
	v_add_f32_e32 v200, 1.0, v200
	v_add_f32_e32 v201, 1.0, v201
	v_rcp_f32_e32 v198, v198
	v_rcp_f32_e32 v199, v199
	v_rcp_f32_e32 v200, v200
	v_rcp_f32_e32 v201, v201
	v_mul_f32_e32 v190, v190, v198
	v_mul_f32_e32 v191, v191, v199
	v_mul_f32_e32 v192, v192, v200
	v_mul_f32_e32 v193, v193, v201
	v_mul_f32_e32 v190, v190, v194
	v_mul_f32_e32 v191, v191, v195
	v_mul_f32_e32 v192, v192, v196
	v_mul_f32_e32 v193, v193, v197
	v_cvt_pk_bf16_f32 v232, v190, v191
	v_cvt_pk_bf16_f32 v233, v192, v193
	v_fma_f32 v190, v150, v122, v118
	v_fma_f32 v191, v151, v123, v119
	v_fma_f32 v192, v152, v124, v120
	v_fma_f32 v193, v153, v125, v121
	v_fma_f32 v194, v146, v106, v102
	v_fma_f32 v195, v147, v107, v103
	v_fma_f32 v196, v148, v108, v104
	v_fma_f32 v197, v149, v109, v105
	v_fmac_f32_e32 v190, v158, v126
	v_fmac_f32_e32 v191, v159, v127
	v_fmac_f32_e32 v192, v160, v128
	v_fmac_f32_e32 v193, v161, v129
	v_fmac_f32_e32 v194, v154, v110
	v_fmac_f32_e32 v195, v155, v111
	v_fmac_f32_e32 v196, v156, v112
	v_fmac_f32_e32 v197, v157, v113
	v_fmac_f32_e32 v190, v142, v114
	v_fmac_f32_e32 v191, v143, v115
	v_fmac_f32_e32 v192, v144, v116
	v_fmac_f32_e32 v193, v145, v117
	v_fmac_f32_e32 v194, v138, v98
	v_fmac_f32_e32 v195, v139, v99
	v_fmac_f32_e32 v196, v140, v100
	v_fmac_f32_e32 v197, v141, v101
	v_mul_f32_e32 v198, 0xbfb8aa3b, v190
	v_mul_f32_e32 v199, 0xbfb8aa3b, v191
	v_mul_f32_e32 v200, 0xbfb8aa3b, v192
	v_mul_f32_e32 v201, 0xbfb8aa3b, v193
	v_exp_f32_e32 v198, v198
	v_exp_f32_e32 v199, v199
	v_exp_f32_e32 v200, v200
	v_exp_f32_e32 v201, v201
	v_add_f32_e32 v198, 1.0, v198
	v_add_f32_e32 v199, 1.0, v199
	v_add_f32_e32 v200, 1.0, v200
	v_add_f32_e32 v201, 1.0, v201
	v_rcp_f32_e32 v198, v198
	v_rcp_f32_e32 v199, v199
	v_rcp_f32_e32 v200, v200
	v_rcp_f32_e32 v201, v201
	v_mul_f32_e32 v190, v190, v198
	v_mul_f32_e32 v191, v191, v199
	v_mul_f32_e32 v192, v192, v200
	v_mul_f32_e32 v193, v193, v201
	v_mul_f32_e32 v190, v190, v194
	v_mul_f32_e32 v191, v191, v195
	v_mul_f32_e32 v192, v192, v196
	v_mul_f32_e32 v193, v193, v197
	v_cvt_pk_bf16_f32 v234, v190, v191
	v_cvt_pk_bf16_f32 v235, v192, v193
	v_cmp_gt_i32_e32 vcc, s3, v230
	s_and_b64 vcc, vcc, s[52:53]
	s_nop 0
	v_permlane16_swap_b32_e32 v232, v234
	v_permlane16_swap_b32_e32 v233, v235
	s_and_saveexec_b64 s[0:1], vcc
	global_store_dwordx4 v187, v[232:235], s[12:13]
	s_mov_b64 exec, s[0:1]
	v_fma_f32 v190, v142, v122, v118
	v_fma_f32 v191, v143, v123, v119
	v_fma_f32 v192, v144, v124, v120
	v_fma_f32 v193, v145, v125, v121
	v_fma_f32 v194, v138, v106, v102
	v_fma_f32 v195, v139, v107, v103
	v_fma_f32 v196, v140, v108, v104
	v_fma_f32 v197, v141, v109, v105
	v_add_u32_e32 v230, 2, v186
	v_add_u32_e32 v231, 0x2c00, v187
	v_fmac_f32_e32 v190, v150, v126
	v_fmac_f32_e32 v191, v151, v127
	v_fmac_f32_e32 v192, v152, v128
	v_fmac_f32_e32 v193, v153, v129
	v_fmac_f32_e32 v194, v146, v110
	v_fmac_f32_e32 v195, v147, v111
	v_fmac_f32_e32 v196, v148, v112
	v_fmac_f32_e32 v197, v149, v113
	v_fmac_f32_e32 v190, v134, v114
	v_fmac_f32_e32 v191, v135, v115
	v_fmac_f32_e32 v192, v136, v116
	v_fmac_f32_e32 v193, v137, v117
	v_fmac_f32_e32 v194, v130, v98
	v_fmac_f32_e32 v195, v131, v99
	v_fmac_f32_e32 v196, v132, v100
	v_fmac_f32_e32 v197, v133, v101
	v_mul_f32_e32 v198, 0xbfb8aa3b, v190
	v_mul_f32_e32 v199, 0xbfb8aa3b, v191
	v_mul_f32_e32 v200, 0xbfb8aa3b, v192
	v_mul_f32_e32 v201, 0xbfb8aa3b, v193
	v_exp_f32_e32 v198, v198
	v_exp_f32_e32 v199, v199
	v_exp_f32_e32 v200, v200
	v_exp_f32_e32 v201, v201
	v_add_f32_e32 v198, 1.0, v198
	v_add_f32_e32 v199, 1.0, v199
	v_add_f32_e32 v200, 1.0, v200
	v_add_f32_e32 v201, 1.0, v201
	v_rcp_f32_e32 v198, v198
	v_rcp_f32_e32 v199, v199
	v_rcp_f32_e32 v200, v200
	v_rcp_f32_e32 v201, v201
	v_mul_f32_e32 v190, v190, v198
	v_mul_f32_e32 v191, v191, v199
	v_mul_f32_e32 v192, v192, v200
	v_mul_f32_e32 v193, v193, v201
	v_mul_f32_e32 v190, v190, v194
	v_mul_f32_e32 v191, v191, v195
	v_mul_f32_e32 v192, v192, v196
	v_mul_f32_e32 v193, v193, v197
	v_cvt_pk_bf16_f32 v232, v190, v191
	v_cvt_pk_bf16_f32 v233, v192, v193
	v_fma_f32 v190, v134, v122, v118
	v_fma_f32 v191, v135, v123, v119
	v_fma_f32 v192, v136, v124, v120
	v_fma_f32 v193, v137, v125, v121
	v_fma_f32 v194, v130, v106, v102
	v_fma_f32 v195, v131, v107, v103
	v_fma_f32 v196, v132, v108, v104
	v_fma_f32 v197, v133, v109, v105
	v_fmac_f32_e32 v190, v142, v126
	v_fmac_f32_e32 v191, v143, v127
	v_fmac_f32_e32 v192, v144, v128
	v_fmac_f32_e32 v193, v145, v129
	v_fmac_f32_e32 v194, v138, v110
	v_fmac_f32_e32 v195, v139, v111
	v_fmac_f32_e32 v196, v140, v112
	v_fmac_f32_e32 v197, v141, v113
	v_fmac_f32_dpp v190, v158, v114 row_ror:15 row_mask:0xf bank_mask:0xf
	v_fmac_f32_dpp v191, v159, v115 row_ror:15 row_mask:0xf bank_mask:0xf
	v_fmac_f32_dpp v192, v160, v116 row_ror:15 row_mask:0xf bank_mask:0xf
	v_fmac_f32_dpp v193, v161, v117 row_ror:15 row_mask:0xf bank_mask:0xf
	v_fmac_f32_dpp v194, v154, v98 row_ror:15 row_mask:0xf bank_mask:0xf
	v_fmac_f32_dpp v195, v155, v99 row_ror:15 row_mask:0xf bank_mask:0xf
	v_fmac_f32_dpp v196, v156, v100 row_ror:15 row_mask:0xf bank_mask:0xf
	v_fmac_f32_dpp v197, v157, v101 row_ror:15 row_mask:0xf bank_mask:0xf
	v_mul_f32_e32 v198, 0xbfb8aa3b, v190
	v_mul_f32_e32 v199, 0xbfb8aa3b, v191
	v_mul_f32_e32 v200, 0xbfb8aa3b, v192
	v_mul_f32_e32 v201, 0xbfb8aa3b, v193
	v_exp_f32_e32 v198, v198
	v_exp_f32_e32 v199, v199
	v_exp_f32_e32 v200, v200
	v_exp_f32_e32 v201, v201
	v_add_f32_e32 v198, 1.0, v198
	v_add_f32_e32 v199, 1.0, v199
	v_add_f32_e32 v200, 1.0, v200
	v_add_f32_e32 v201, 1.0, v201
	v_rcp_f32_e32 v198, v198
	v_rcp_f32_e32 v199, v199
	v_rcp_f32_e32 v200, v200
	v_rcp_f32_e32 v201, v201
	v_mul_f32_e32 v190, v190, v198
	v_mul_f32_e32 v191, v191, v199
	v_mul_f32_e32 v192, v192, v200
	v_mul_f32_e32 v193, v193, v201
	v_mul_f32_e32 v190, v190, v194
	v_mul_f32_e32 v191, v191, v195
	v_mul_f32_e32 v192, v192, v196
	v_mul_f32_e32 v193, v193, v197
	v_cvt_pk_bf16_f32 v234, v190, v191
	v_cvt_pk_bf16_f32 v235, v192, v193
	v_cmp_gt_i32_e32 vcc, s3, v230
	s_and_b64 vcc, vcc, s[54:55]
	s_nop 0
	v_permlane16_swap_b32_e32 v232, v234
	v_permlane16_swap_b32_e32 v233, v235
	s_and_saveexec_b64 s[0:1], vcc
	global_store_dwordx4 v231, v[232:235], s[12:13]
	s_mov_b64 exec, s[0:1]
	ds_read_b128 v[130:133], v188 offset:64
	ds_read_b128 v[134:137], v188 offset:192
	ds_read_b128 v[138:141], v188 offset:320
	ds_read_b128 v[142:145], v188 offset:448
	ds_read_b128 v[146:149], v188 offset:576
	ds_read_b128 v[150:153], v188 offset:704
	ds_read_b128 v[154:157], v188 offset:832
	ds_read_b128 v[158:161], v188 offset:960
	v_fma_f32 v190, v94, v122, v118
	v_fma_f32 v191, v95, v123, v119
	v_fma_f32 v192, v96, v124, v120
	v_fma_f32 v193, v97, v125, v121
	v_fma_f32 v194, v90, v106, v102
	v_fma_f32 v195, v91, v107, v103
	v_fma_f32 v196, v92, v108, v104
	v_fma_f32 v197, v93, v109, v105
	v_add_u32_e32 v230, 0x7c, v186
	v_add_u32_e32 v231, 0xaa800, v187
	v_fmac_f32_dpp v190, v70, v126 row_ror:1 row_mask:0xf bank_mask:0xf
	v_fmac_f32_dpp v191, v71, v127 row_ror:1 row_mask:0xf bank_mask:0xf
	v_fmac_f32_dpp v192, v72, v128 row_ror:1 row_mask:0xf bank_mask:0xf
	v_fmac_f32_dpp v193, v73, v129 row_ror:1 row_mask:0xf bank_mask:0xf
	v_fmac_f32_dpp v194, v66, v110 row_ror:1 row_mask:0xf bank_mask:0xf
	v_fmac_f32_dpp v195, v67, v111 row_ror:1 row_mask:0xf bank_mask:0xf
	v_fmac_f32_dpp v196, v68, v112 row_ror:1 row_mask:0xf bank_mask:0xf
	v_fmac_f32_dpp v197, v69, v113 row_ror:1 row_mask:0xf bank_mask:0xf
	v_fmac_f32_e32 v190, v86, v114
	v_fmac_f32_e32 v191, v87, v115
	v_fmac_f32_e32 v192, v88, v116
	v_fmac_f32_e32 v193, v89, v117
	v_fmac_f32_e32 v194, v82, v98
	v_fmac_f32_e32 v195, v83, v99
	v_fmac_f32_e32 v196, v84, v100
	v_fmac_f32_e32 v197, v85, v101
	v_mul_f32_e32 v198, 0xbfb8aa3b, v190
	v_mul_f32_e32 v199, 0xbfb8aa3b, v191
	v_mul_f32_e32 v200, 0xbfb8aa3b, v192
	v_mul_f32_e32 v201, 0xbfb8aa3b, v193
	v_exp_f32_e32 v198, v198
	v_exp_f32_e32 v199, v199
	v_exp_f32_e32 v200, v200
	v_exp_f32_e32 v201, v201
	v_add_f32_e32 v198, 1.0, v198
	v_add_f32_e32 v199, 1.0, v199
	v_add_f32_e32 v200, 1.0, v200
	v_add_f32_e32 v201, 1.0, v201
	v_rcp_f32_e32 v198, v198
	v_rcp_f32_e32 v199, v199
	v_rcp_f32_e32 v200, v200
	v_rcp_f32_e32 v201, v201
	v_mul_f32_e32 v190, v190, v198
	v_mul_f32_e32 v191, v191, v199
	v_mul_f32_e32 v192, v192, v200
	v_mul_f32_e32 v193, v193, v201
	v_mul_f32_e32 v190, v190, v194
	v_mul_f32_e32 v191, v191, v195
	v_mul_f32_e32 v192, v192, v196
	v_mul_f32_e32 v193, v193, v197
	v_cvt_pk_bf16_f32 v232, v190, v191
	v_cvt_pk_bf16_f32 v233, v192, v193
	v_fma_f32 v190, v86, v122, v118
	v_fma_f32 v191, v87, v123, v119
	v_fma_f32 v192, v88, v124, v120
	v_fma_f32 v193, v89, v125, v121
	v_fma_f32 v194, v82, v106, v102
	v_fma_f32 v195, v83, v107, v103
	v_fma_f32 v196, v84, v108, v104
	v_fma_f32 v197, v85, v109, v105
	v_fmac_f32_e32 v190, v94, v126
	v_fmac_f32_e32 v191, v95, v127
	v_fmac_f32_e32 v192, v96, v128
	v_fmac_f32_e32 v193, v97, v129
	v_fmac_f32_e32 v194, v90, v110
	v_fmac_f32_e32 v195, v91, v111
	v_fmac_f32_e32 v196, v92, v112
	v_fmac_f32_e32 v197, v93, v113
	v_fmac_f32_e32 v190, v78, v114
	v_fmac_f32_e32 v191, v79, v115
	v_fmac_f32_e32 v192, v80, v116
	v_fmac_f32_e32 v193, v81, v117
	v_fmac_f32_e32 v194, v74, v98
	v_fmac_f32_e32 v195, v75, v99
	v_fmac_f32_e32 v196, v76, v100
	v_fmac_f32_e32 v197, v77, v101
	v_mul_f32_e32 v198, 0xbfb8aa3b, v190
	v_mul_f32_e32 v199, 0xbfb8aa3b, v191
	v_mul_f32_e32 v200, 0xbfb8aa3b, v192
	v_mul_f32_e32 v201, 0xbfb8aa3b, v193
	v_exp_f32_e32 v198, v198
	v_exp_f32_e32 v199, v199
	v_exp_f32_e32 v200, v200
	v_exp_f32_e32 v201, v201
	v_add_f32_e32 v198, 1.0, v198
	v_add_f32_e32 v199, 1.0, v199
	v_add_f32_e32 v200, 1.0, v200
	v_add_f32_e32 v201, 1.0, v201
	v_rcp_f32_e32 v198, v198
	v_rcp_f32_e32 v199, v199
	v_rcp_f32_e32 v200, v200
	v_rcp_f32_e32 v201, v201
	v_mul_f32_e32 v190, v190, v198
	v_mul_f32_e32 v191, v191, v199
	v_mul_f32_e32 v192, v192, v200
	v_mul_f32_e32 v193, v193, v201
	v_mul_f32_e32 v190, v190, v194
	v_mul_f32_e32 v191, v191, v195
	v_mul_f32_e32 v192, v192, v196
	v_mul_f32_e32 v193, v193, v197
	v_cvt_pk_bf16_f32 v234, v190, v191
	v_cvt_pk_bf16_f32 v235, v192, v193
	v_cmp_gt_i32_e32 vcc, s3, v230
	s_and_b64 vcc, vcc, s[52:53]
	s_nop 0
	v_permlane16_swap_b32_e32 v232, v234
	v_permlane16_swap_b32_e32 v233, v235
	s_and_saveexec_b64 s[0:1], vcc
	global_store_dwordx4 v231, v[232:235], s[12:13]
	s_mov_b64 exec, s[0:1]
	v_fma_f32 v190, v78, v122, v118
	v_fma_f32 v191, v79, v123, v119
	v_fma_f32 v192, v80, v124, v120
	v_fma_f32 v193, v81, v125, v121
	v_fma_f32 v194, v74, v106, v102
	v_fma_f32 v195, v75, v107, v103
	v_fma_f32 v196, v76, v108, v104
	v_fma_f32 v197, v77, v109, v105
	v_add_u32_e32 v230, 0x7e, v186
	v_add_u32_e32 v231, 0xad400, v187
	v_fmac_f32_e32 v190, v86, v126
	v_fmac_f32_e32 v191, v87, v127
	v_fmac_f32_e32 v192, v88, v128
	v_fmac_f32_e32 v193, v89, v129
	v_fmac_f32_e32 v194, v82, v110
	v_fmac_f32_e32 v195, v83, v111
	v_fmac_f32_e32 v196, v84, v112
	v_fmac_f32_e32 v197, v85, v113
	v_fmac_f32_e32 v190, v70, v114
	v_fmac_f32_e32 v191, v71, v115
	v_fmac_f32_e32 v192, v72, v116
	v_fmac_f32_e32 v193, v73, v117
	v_fmac_f32_e32 v194, v66, v98
	v_fmac_f32_e32 v195, v67, v99
	v_fmac_f32_e32 v196, v68, v100
	v_fmac_f32_e32 v197, v69, v101
	v_mul_f32_e32 v198, 0xbfb8aa3b, v190
	v_mul_f32_e32 v199, 0xbfb8aa3b, v191
	v_mul_f32_e32 v200, 0xbfb8aa3b, v192
	v_mul_f32_e32 v201, 0xbfb8aa3b, v193
	v_exp_f32_e32 v198, v198
	v_exp_f32_e32 v199, v199
	v_exp_f32_e32 v200, v200
	v_exp_f32_e32 v201, v201
	v_add_f32_e32 v198, 1.0, v198
	v_add_f32_e32 v199, 1.0, v199
	v_add_f32_e32 v200, 1.0, v200
	v_add_f32_e32 v201, 1.0, v201
	v_rcp_f32_e32 v198, v198
	v_rcp_f32_e32 v199, v199
	v_rcp_f32_e32 v200, v200
	v_rcp_f32_e32 v201, v201
	v_mul_f32_e32 v190, v190, v198
	v_mul_f32_e32 v191, v191, v199
	v_mul_f32_e32 v192, v192, v200
	v_mul_f32_e32 v193, v193, v201
	v_mul_f32_e32 v190, v190, v194
	v_mul_f32_e32 v191, v191, v195
	v_mul_f32_e32 v192, v192, v196
	v_mul_f32_e32 v193, v193, v197
	v_cvt_pk_bf16_f32 v232, v190, v191
	v_cvt_pk_bf16_f32 v233, v192, v193
	v_fma_f32 v190, v70, v122, v118
	v_fma_f32 v191, v71, v123, v119
	v_fma_f32 v192, v72, v124, v120
	v_fma_f32 v193, v73, v125, v121
	v_fma_f32 v194, v66, v106, v102
	v_fma_f32 v195, v67, v107, v103
	v_fma_f32 v196, v68, v108, v104
	v_fma_f32 v197, v69, v109, v105
	v_fmac_f32_e32 v190, v78, v126
	v_fmac_f32_e32 v191, v79, v127
	v_fmac_f32_e32 v192, v80, v128
	v_fmac_f32_e32 v193, v81, v129
	v_fmac_f32_e32 v194, v74, v110
	v_fmac_f32_e32 v195, v75, v111
	v_fmac_f32_e32 v196, v76, v112
	v_fmac_f32_e32 v197, v77, v113
	v_fmac_f32_dpp v190, v94, v114 row_ror:15 row_mask:0xf bank_mask:0xf
	v_fmac_f32_dpp v191, v95, v115 row_ror:15 row_mask:0xf bank_mask:0xf
	v_fmac_f32_dpp v192, v96, v116 row_ror:15 row_mask:0xf bank_mask:0xf
	v_fmac_f32_dpp v193, v97, v117 row_ror:15 row_mask:0xf bank_mask:0xf
	v_fmac_f32_dpp v194, v90, v98 row_ror:15 row_mask:0xf bank_mask:0xf
	v_fmac_f32_dpp v195, v91, v99 row_ror:15 row_mask:0xf bank_mask:0xf
	v_fmac_f32_dpp v196, v92, v100 row_ror:15 row_mask:0xf bank_mask:0xf
	v_fmac_f32_dpp v197, v93, v101 row_ror:15 row_mask:0xf bank_mask:0xf
	v_mul_f32_e32 v198, 0xbfb8aa3b, v190
	v_mul_f32_e32 v199, 0xbfb8aa3b, v191
	v_mul_f32_e32 v200, 0xbfb8aa3b, v192
	v_mul_f32_e32 v201, 0xbfb8aa3b, v193
	v_exp_f32_e32 v198, v198
	v_exp_f32_e32 v199, v199
	v_exp_f32_e32 v200, v200
	v_exp_f32_e32 v201, v201
	v_add_f32_e32 v198, 1.0, v198
	v_add_f32_e32 v199, 1.0, v199
	v_add_f32_e32 v200, 1.0, v200
	v_add_f32_e32 v201, 1.0, v201
	v_rcp_f32_e32 v198, v198
	v_rcp_f32_e32 v199, v199
	v_rcp_f32_e32 v200, v200
	v_rcp_f32_e32 v201, v201
	v_mul_f32_e32 v190, v190, v198
	v_mul_f32_e32 v191, v191, v199
	v_mul_f32_e32 v192, v192, v200
	v_mul_f32_e32 v193, v193, v201
	v_mul_f32_e32 v190, v190, v194
	v_mul_f32_e32 v191, v191, v195
	v_mul_f32_e32 v192, v192, v196
	v_mul_f32_e32 v193, v193, v197
	v_cvt_pk_bf16_f32 v234, v190, v191
	v_cvt_pk_bf16_f32 v235, v192, v193
	v_cmp_gt_i32_e32 vcc, s3, v230
	s_and_b64 vcc, vcc, s[54:55]
	s_nop 0
	v_permlane16_swap_b32_e32 v232, v234
	v_permlane16_swap_b32_e32 v233, v235
	s_and_saveexec_b64 s[0:1], vcc
	global_store_dwordx4 v231, v[232:235], s[12:13]
	s_mov_b64 exec, s[0:1]
	s_waitcnt lgkmcnt(0)
	v_fma_f32 v190, v62, v134, v142
	v_fma_f32 v191, v63, v135, v143
	v_fma_f32 v192, v64, v136, v144
	v_fma_f32 v193, v65, v137, v145
	v_fma_f32 v194, v58, v150, v158
	v_fma_f32 v195, v59, v151, v159
	v_fma_f32 v196, v60, v152, v160
	v_fma_f32 v197, v61, v153, v161
	v_add_u32_e32 v230, 0, v186
	v_fmac_f32_dpp v190, v38, v130 row_ror:1 row_mask:0xf bank_mask:0xf
	v_fmac_f32_dpp v191, v39, v131 row_ror:1 row_mask:0xf bank_mask:0xf
	v_fmac_f32_dpp v192, v40, v132 row_ror:1 row_mask:0xf bank_mask:0xf
	v_fmac_f32_dpp v193, v41, v133 row_ror:1 row_mask:0xf bank_mask:0xf
	v_fmac_f32_dpp v194, v34, v146 row_ror:1 row_mask:0xf bank_mask:0xf
	v_fmac_f32_dpp v195, v35, v147 row_ror:1 row_mask:0xf bank_mask:0xf
	v_fmac_f32_dpp v196, v36, v148 row_ror:1 row_mask:0xf bank_mask:0xf
	v_fmac_f32_dpp v197, v37, v149 row_ror:1 row_mask:0xf bank_mask:0xf
	v_fmac_f32_e32 v190, v54, v138
	v_fmac_f32_e32 v191, v55, v139
	v_fmac_f32_e32 v192, v56, v140
	v_fmac_f32_e32 v193, v57, v141
	v_fmac_f32_e32 v194, v50, v154
	v_fmac_f32_e32 v195, v51, v155
	v_fmac_f32_e32 v196, v52, v156
	v_fmac_f32_e32 v197, v53, v157
	v_mul_f32_e32 v198, 0xbfb8aa3b, v190
	v_mul_f32_e32 v199, 0xbfb8aa3b, v191
	v_mul_f32_e32 v200, 0xbfb8aa3b, v192
	v_mul_f32_e32 v201, 0xbfb8aa3b, v193
	v_exp_f32_e32 v198, v198
	v_exp_f32_e32 v199, v199
	v_exp_f32_e32 v200, v200
	v_exp_f32_e32 v201, v201
	v_add_f32_e32 v198, 1.0, v198
	v_add_f32_e32 v199, 1.0, v199
	v_add_f32_e32 v200, 1.0, v200
	v_add_f32_e32 v201, 1.0, v201
	v_rcp_f32_e32 v198, v198
	v_rcp_f32_e32 v199, v199
	v_rcp_f32_e32 v200, v200
	v_rcp_f32_e32 v201, v201
	v_mul_f32_e32 v190, v190, v198
	v_mul_f32_e32 v191, v191, v199
	v_mul_f32_e32 v192, v192, v200
	v_mul_f32_e32 v193, v193, v201
	v_mul_f32_e32 v190, v190, v194
	v_mul_f32_e32 v191, v191, v195
	v_mul_f32_e32 v192, v192, v196
	v_mul_f32_e32 v193, v193, v197
	v_cvt_pk_bf16_f32 v232, v190, v191
	v_cvt_pk_bf16_f32 v233, v192, v193
	v_fma_f32 v190, v54, v134, v142
	v_fma_f32 v191, v55, v135, v143
	v_fma_f32 v192, v56, v136, v144
	v_fma_f32 v193, v57, v137, v145
	v_fma_f32 v194, v50, v150, v158
	v_fma_f32 v195, v51, v151, v159
	v_fma_f32 v196, v52, v152, v160
	v_fma_f32 v197, v53, v153, v161
	v_fmac_f32_e32 v190, v62, v130
	v_fmac_f32_e32 v191, v63, v131
	v_fmac_f32_e32 v192, v64, v132
	v_fmac_f32_e32 v193, v65, v133
	v_fmac_f32_e32 v194, v58, v146
	v_fmac_f32_e32 v195, v59, v147
	v_fmac_f32_e32 v196, v60, v148
	v_fmac_f32_e32 v197, v61, v149
	v_fmac_f32_e32 v190, v46, v138
	v_fmac_f32_e32 v191, v47, v139
	v_fmac_f32_e32 v192, v48, v140
	v_fmac_f32_e32 v193, v49, v141
	v_fmac_f32_e32 v194, v42, v154
	v_fmac_f32_e32 v195, v43, v155
	v_fmac_f32_e32 v196, v44, v156
	v_fmac_f32_e32 v197, v45, v157
	v_mul_f32_e32 v198, 0xbfb8aa3b, v190
	v_mul_f32_e32 v199, 0xbfb8aa3b, v191
	v_mul_f32_e32 v200, 0xbfb8aa3b, v192
	v_mul_f32_e32 v201, 0xbfb8aa3b, v193
	v_exp_f32_e32 v198, v198
	v_exp_f32_e32 v199, v199
	v_exp_f32_e32 v200, v200
	v_exp_f32_e32 v201, v201
	v_add_f32_e32 v198, 1.0, v198
	v_add_f32_e32 v199, 1.0, v199
	v_add_f32_e32 v200, 1.0, v200
	v_add_f32_e32 v201, 1.0, v201
	v_rcp_f32_e32 v198, v198
	v_rcp_f32_e32 v199, v199
	v_rcp_f32_e32 v200, v200
	v_rcp_f32_e32 v201, v201
	v_mul_f32_e32 v190, v190, v198
	v_mul_f32_e32 v191, v191, v199
	v_mul_f32_e32 v192, v192, v200
	v_mul_f32_e32 v193, v193, v201
	v_mul_f32_e32 v190, v190, v194
	v_mul_f32_e32 v191, v191, v195
	v_mul_f32_e32 v192, v192, v196
	v_mul_f32_e32 v193, v193, v197
	v_cvt_pk_bf16_f32 v234, v190, v191
	v_cvt_pk_bf16_f32 v235, v192, v193
	v_cmp_gt_i32_e32 vcc, s3, v230
	s_and_b64 vcc, vcc, s[52:53]
	s_nop 0
	v_permlane16_swap_b32_e32 v232, v234
	v_permlane16_swap_b32_e32 v233, v235
	s_and_saveexec_b64 s[0:1], vcc
	global_store_dwordx4 v187, v[232:235], s[12:13] offset:128
	s_mov_b64 exec, s[0:1]
	v_fma_f32 v190, v46, v134, v142
	v_fma_f32 v191, v47, v135, v143
	v_fma_f32 v192, v48, v136, v144
	v_fma_f32 v193, v49, v137, v145
	v_fma_f32 v194, v42, v150, v158
	v_fma_f32 v195, v43, v151, v159
	v_fma_f32 v196, v44, v152, v160
	v_fma_f32 v197, v45, v153, v161
	v_add_u32_e32 v230, 2, v186
	v_add_u32_e32 v231, 0x2c00, v187
	v_fmac_f32_e32 v190, v54, v130
	v_fmac_f32_e32 v191, v55, v131
	v_fmac_f32_e32 v192, v56, v132
	v_fmac_f32_e32 v193, v57, v133
	v_fmac_f32_e32 v194, v50, v146
	v_fmac_f32_e32 v195, v51, v147
	v_fmac_f32_e32 v196, v52, v148
	v_fmac_f32_e32 v197, v53, v149
	v_fmac_f32_e32 v190, v38, v138
	v_fmac_f32_e32 v191, v39, v139
	v_fmac_f32_e32 v192, v40, v140
	v_fmac_f32_e32 v193, v41, v141
	v_fmac_f32_e32 v194, v34, v154
	v_fmac_f32_e32 v195, v35, v155
	v_fmac_f32_e32 v196, v36, v156
	v_fmac_f32_e32 v197, v37, v157
	v_mul_f32_e32 v198, 0xbfb8aa3b, v190
	v_mul_f32_e32 v199, 0xbfb8aa3b, v191
	v_mul_f32_e32 v200, 0xbfb8aa3b, v192
	v_mul_f32_e32 v201, 0xbfb8aa3b, v193
	v_exp_f32_e32 v198, v198
	v_exp_f32_e32 v199, v199
	v_exp_f32_e32 v200, v200
	v_exp_f32_e32 v201, v201
	v_add_f32_e32 v198, 1.0, v198
	v_add_f32_e32 v199, 1.0, v199
	v_add_f32_e32 v200, 1.0, v200
	v_add_f32_e32 v201, 1.0, v201
	v_rcp_f32_e32 v198, v198
	v_rcp_f32_e32 v199, v199
	v_rcp_f32_e32 v200, v200
	v_rcp_f32_e32 v201, v201
	v_mul_f32_e32 v190, v190, v198
	v_mul_f32_e32 v191, v191, v199
	v_mul_f32_e32 v192, v192, v200
	v_mul_f32_e32 v193, v193, v201
	v_mul_f32_e32 v190, v190, v194
	v_mul_f32_e32 v191, v191, v195
	v_mul_f32_e32 v192, v192, v196
	v_mul_f32_e32 v193, v193, v197
	v_cvt_pk_bf16_f32 v232, v190, v191
	v_cvt_pk_bf16_f32 v233, v192, v193
	v_fma_f32 v190, v38, v134, v142
	v_fma_f32 v191, v39, v135, v143
	v_fma_f32 v192, v40, v136, v144
	v_fma_f32 v193, v41, v137, v145
	v_fma_f32 v194, v34, v150, v158
	v_fma_f32 v195, v35, v151, v159
	v_fma_f32 v196, v36, v152, v160
	v_fma_f32 v197, v37, v153, v161
	v_fmac_f32_e32 v190, v46, v130
	v_fmac_f32_e32 v191, v47, v131
	v_fmac_f32_e32 v192, v48, v132
	v_fmac_f32_e32 v193, v49, v133
	v_fmac_f32_e32 v194, v42, v146
	v_fmac_f32_e32 v195, v43, v147
	v_fmac_f32_e32 v196, v44, v148
	v_fmac_f32_e32 v197, v45, v149
	v_fmac_f32_dpp v190, v62, v138 row_ror:15 row_mask:0xf bank_mask:0xf
	v_fmac_f32_dpp v191, v63, v139 row_ror:15 row_mask:0xf bank_mask:0xf
	v_fmac_f32_dpp v192, v64, v140 row_ror:15 row_mask:0xf bank_mask:0xf
	v_fmac_f32_dpp v193, v65, v141 row_ror:15 row_mask:0xf bank_mask:0xf
	v_fmac_f32_dpp v194, v58, v154 row_ror:15 row_mask:0xf bank_mask:0xf
	v_fmac_f32_dpp v195, v59, v155 row_ror:15 row_mask:0xf bank_mask:0xf
	v_fmac_f32_dpp v196, v60, v156 row_ror:15 row_mask:0xf bank_mask:0xf
	v_fmac_f32_dpp v197, v61, v157 row_ror:15 row_mask:0xf bank_mask:0xf
	v_mul_f32_e32 v198, 0xbfb8aa3b, v190
	v_mul_f32_e32 v199, 0xbfb8aa3b, v191
	v_mul_f32_e32 v200, 0xbfb8aa3b, v192
	v_mul_f32_e32 v201, 0xbfb8aa3b, v193
	v_exp_f32_e32 v198, v198
	v_exp_f32_e32 v199, v199
	v_exp_f32_e32 v200, v200
	v_exp_f32_e32 v201, v201
	v_add_f32_e32 v198, 1.0, v198
	v_add_f32_e32 v199, 1.0, v199
	v_add_f32_e32 v200, 1.0, v200
	v_add_f32_e32 v201, 1.0, v201
	v_rcp_f32_e32 v198, v198
	v_rcp_f32_e32 v199, v199
	v_rcp_f32_e32 v200, v200
	v_rcp_f32_e32 v201, v201
	v_mul_f32_e32 v190, v190, v198
	v_mul_f32_e32 v191, v191, v199
	v_mul_f32_e32 v192, v192, v200
	v_mul_f32_e32 v193, v193, v201
	v_mul_f32_e32 v190, v190, v194
	v_mul_f32_e32 v191, v191, v195
	v_mul_f32_e32 v192, v192, v196
	v_mul_f32_e32 v193, v193, v197
	v_cvt_pk_bf16_f32 v234, v190, v191
	v_cvt_pk_bf16_f32 v235, v192, v193
	v_cmp_gt_i32_e32 vcc, s3, v230
	s_and_b64 vcc, vcc, s[54:55]
	s_nop 0
	v_permlane16_swap_b32_e32 v232, v234
	v_permlane16_swap_b32_e32 v233, v235
	s_and_saveexec_b64 s[0:1], vcc
	global_store_dwordx4 v231, v[232:235], s[12:13] offset:128
	s_mov_b64 exec, s[0:1]
	v_fma_f32 v190, v30, v134, v142
	v_fma_f32 v191, v31, v135, v143
	v_fma_f32 v192, v32, v136, v144
	v_fma_f32 v193, v33, v137, v145
	v_fma_f32 v194, v26, v150, v158
	v_fma_f32 v195, v27, v151, v159
	v_fma_f32 v196, v28, v152, v160
	v_fma_f32 v197, v29, v153, v161
	v_add_u32_e32 v230, 0x7c, v186
	v_add_u32_e32 v231, 0xaa800, v187
	v_fmac_f32_dpp v190, v6, v130 row_ror:1 row_mask:0xf bank_mask:0xf
	v_fmac_f32_dpp v191, v7, v131 row_ror:1 row_mask:0xf bank_mask:0xf
	v_fmac_f32_dpp v192, v8, v132 row_ror:1 row_mask:0xf bank_mask:0xf
	v_fmac_f32_dpp v193, v9, v133 row_ror:1 row_mask:0xf bank_mask:0xf
	v_fmac_f32_dpp v194, v2, v146 row_ror:1 row_mask:0xf bank_mask:0xf
	v_fmac_f32_dpp v195, v3, v147 row_ror:1 row_mask:0xf bank_mask:0xf
	v_fmac_f32_dpp v196, v4, v148 row_ror:1 row_mask:0xf bank_mask:0xf
	v_fmac_f32_dpp v197, v5, v149 row_ror:1 row_mask:0xf bank_mask:0xf
	v_fmac_f32_e32 v190, v22, v138
	v_fmac_f32_e32 v191, v23, v139
	v_fmac_f32_e32 v192, v24, v140
	v_fmac_f32_e32 v193, v25, v141
	v_fmac_f32_e32 v194, v18, v154
	v_fmac_f32_e32 v195, v19, v155
	v_fmac_f32_e32 v196, v20, v156
	v_fmac_f32_e32 v197, v21, v157
	v_mul_f32_e32 v198, 0xbfb8aa3b, v190
	v_mul_f32_e32 v199, 0xbfb8aa3b, v191
	v_mul_f32_e32 v200, 0xbfb8aa3b, v192
	v_mul_f32_e32 v201, 0xbfb8aa3b, v193
	v_exp_f32_e32 v198, v198
	v_exp_f32_e32 v199, v199
	v_exp_f32_e32 v200, v200
	v_exp_f32_e32 v201, v201
	v_add_f32_e32 v198, 1.0, v198
	v_add_f32_e32 v199, 1.0, v199
	v_add_f32_e32 v200, 1.0, v200
	v_add_f32_e32 v201, 1.0, v201
	v_rcp_f32_e32 v198, v198
	v_rcp_f32_e32 v199, v199
	v_rcp_f32_e32 v200, v200
	v_rcp_f32_e32 v201, v201
	v_mul_f32_e32 v190, v190, v198
	v_mul_f32_e32 v191, v191, v199
	v_mul_f32_e32 v192, v192, v200
	v_mul_f32_e32 v193, v193, v201
	v_mul_f32_e32 v190, v190, v194
	v_mul_f32_e32 v191, v191, v195
	v_mul_f32_e32 v192, v192, v196
	v_mul_f32_e32 v193, v193, v197
	v_cvt_pk_bf16_f32 v232, v190, v191
	v_cvt_pk_bf16_f32 v233, v192, v193
	v_fma_f32 v190, v22, v134, v142
	v_fma_f32 v191, v23, v135, v143
	v_fma_f32 v192, v24, v136, v144
	v_fma_f32 v193, v25, v137, v145
	v_fma_f32 v194, v18, v150, v158
	v_fma_f32 v195, v19, v151, v159
	v_fma_f32 v196, v20, v152, v160
	v_fma_f32 v197, v21, v153, v161
	v_fmac_f32_e32 v190, v30, v130
	v_fmac_f32_e32 v191, v31, v131
	v_fmac_f32_e32 v192, v32, v132
	v_fmac_f32_e32 v193, v33, v133
	v_fmac_f32_e32 v194, v26, v146
	v_fmac_f32_e32 v195, v27, v147
	v_fmac_f32_e32 v196, v28, v148
	v_fmac_f32_e32 v197, v29, v149
	v_fmac_f32_e32 v190, v14, v138
	v_fmac_f32_e32 v191, v15, v139
	v_fmac_f32_e32 v192, v16, v140
	v_fmac_f32_e32 v193, v17, v141
	v_fmac_f32_e32 v194, v10, v154
	v_fmac_f32_e32 v195, v11, v155
	v_fmac_f32_e32 v196, v12, v156
	v_fmac_f32_e32 v197, v13, v157
	v_mul_f32_e32 v198, 0xbfb8aa3b, v190
	v_mul_f32_e32 v199, 0xbfb8aa3b, v191
	v_mul_f32_e32 v200, 0xbfb8aa3b, v192
	v_mul_f32_e32 v201, 0xbfb8aa3b, v193
	v_exp_f32_e32 v198, v198
	v_exp_f32_e32 v199, v199
	v_exp_f32_e32 v200, v200
	v_exp_f32_e32 v201, v201
	v_add_f32_e32 v198, 1.0, v198
	v_add_f32_e32 v199, 1.0, v199
	v_add_f32_e32 v200, 1.0, v200
	v_add_f32_e32 v201, 1.0, v201
	v_rcp_f32_e32 v198, v198
	v_rcp_f32_e32 v199, v199
	v_rcp_f32_e32 v200, v200
	v_rcp_f32_e32 v201, v201
	v_mul_f32_e32 v190, v190, v198
	v_mul_f32_e32 v191, v191, v199
	v_mul_f32_e32 v192, v192, v200
	v_mul_f32_e32 v193, v193, v201
	v_mul_f32_e32 v190, v190, v194
	v_mul_f32_e32 v191, v191, v195
	v_mul_f32_e32 v192, v192, v196
	v_mul_f32_e32 v193, v193, v197
	v_cvt_pk_bf16_f32 v234, v190, v191
	v_cvt_pk_bf16_f32 v235, v192, v193
	v_cmp_gt_i32_e32 vcc, s3, v230
	s_and_b64 vcc, vcc, s[52:53]
	s_nop 0
	v_permlane16_swap_b32_e32 v232, v234
	v_permlane16_swap_b32_e32 v233, v235
	s_and_saveexec_b64 s[0:1], vcc
	global_store_dwordx4 v231, v[232:235], s[12:13] offset:128
	s_mov_b64 exec, s[0:1]
	v_fma_f32 v190, v14, v134, v142
	v_fma_f32 v191, v15, v135, v143
	v_fma_f32 v192, v16, v136, v144
	v_fma_f32 v193, v17, v137, v145
	v_fma_f32 v194, v10, v150, v158
	v_fma_f32 v195, v11, v151, v159
	v_fma_f32 v196, v12, v152, v160
	v_fma_f32 v197, v13, v153, v161
	v_add_u32_e32 v230, 0x7e, v186
	v_add_u32_e32 v231, 0xad400, v187
	v_fmac_f32_e32 v190, v22, v130
	v_fmac_f32_e32 v191, v23, v131
	v_fmac_f32_e32 v192, v24, v132
	v_fmac_f32_e32 v193, v25, v133
	v_fmac_f32_e32 v194, v18, v146
	v_fmac_f32_e32 v195, v19, v147
	v_fmac_f32_e32 v196, v20, v148
	v_fmac_f32_e32 v197, v21, v149
	v_fmac_f32_e32 v190, v6, v138
	v_fmac_f32_e32 v191, v7, v139
	v_fmac_f32_e32 v192, v8, v140
	v_fmac_f32_e32 v193, v9, v141
	v_fmac_f32_e32 v194, v2, v154
	v_fmac_f32_e32 v195, v3, v155
	v_fmac_f32_e32 v196, v4, v156
	v_fmac_f32_e32 v197, v5, v157
	v_mul_f32_e32 v198, 0xbfb8aa3b, v190
	v_mul_f32_e32 v199, 0xbfb8aa3b, v191
	v_mul_f32_e32 v200, 0xbfb8aa3b, v192
	v_mul_f32_e32 v201, 0xbfb8aa3b, v193
	v_exp_f32_e32 v198, v198
	v_exp_f32_e32 v199, v199
	v_exp_f32_e32 v200, v200
	v_exp_f32_e32 v201, v201
	v_add_f32_e32 v198, 1.0, v198
	v_add_f32_e32 v199, 1.0, v199
	v_add_f32_e32 v200, 1.0, v200
	v_add_f32_e32 v201, 1.0, v201
	v_rcp_f32_e32 v198, v198
	v_rcp_f32_e32 v199, v199
	v_rcp_f32_e32 v200, v200
	v_rcp_f32_e32 v201, v201
	v_mul_f32_e32 v190, v190, v198
	v_mul_f32_e32 v191, v191, v199
	v_mul_f32_e32 v192, v192, v200
	v_mul_f32_e32 v193, v193, v201
	v_mul_f32_e32 v190, v190, v194
	v_mul_f32_e32 v191, v191, v195
	v_mul_f32_e32 v192, v192, v196
	v_mul_f32_e32 v193, v193, v197
	v_cvt_pk_bf16_f32 v232, v190, v191
	v_cvt_pk_bf16_f32 v233, v192, v193
	v_fma_f32 v190, v6, v134, v142
	v_fma_f32 v191, v7, v135, v143
	v_fma_f32 v192, v8, v136, v144
	v_fma_f32 v193, v9, v137, v145
	v_fma_f32 v194, v2, v150, v158
	v_fma_f32 v195, v3, v151, v159
	v_fma_f32 v196, v4, v152, v160
	v_fma_f32 v197, v5, v153, v161
	v_fmac_f32_e32 v190, v14, v130
	v_fmac_f32_e32 v191, v15, v131
	v_fmac_f32_e32 v192, v16, v132
	v_fmac_f32_e32 v193, v17, v133
	v_fmac_f32_e32 v194, v10, v146
	v_fmac_f32_e32 v195, v11, v147
	v_fmac_f32_e32 v196, v12, v148
	v_fmac_f32_e32 v197, v13, v149
	v_fmac_f32_dpp v190, v30, v138 row_ror:15 row_mask:0xf bank_mask:0xf
	v_fmac_f32_dpp v191, v31, v139 row_ror:15 row_mask:0xf bank_mask:0xf
	v_fmac_f32_dpp v192, v32, v140 row_ror:15 row_mask:0xf bank_mask:0xf
	v_fmac_f32_dpp v193, v33, v141 row_ror:15 row_mask:0xf bank_mask:0xf
	v_fmac_f32_dpp v194, v26, v154 row_ror:15 row_mask:0xf bank_mask:0xf
	v_fmac_f32_dpp v195, v27, v155 row_ror:15 row_mask:0xf bank_mask:0xf
	v_fmac_f32_dpp v196, v28, v156 row_ror:15 row_mask:0xf bank_mask:0xf
	v_fmac_f32_dpp v197, v29, v157 row_ror:15 row_mask:0xf bank_mask:0xf
	v_mul_f32_e32 v198, 0xbfb8aa3b, v190
	v_mul_f32_e32 v199, 0xbfb8aa3b, v191
	v_mul_f32_e32 v200, 0xbfb8aa3b, v192
	v_mul_f32_e32 v201, 0xbfb8aa3b, v193
	v_exp_f32_e32 v198, v198
	v_exp_f32_e32 v199, v199
	v_exp_f32_e32 v200, v200
	v_exp_f32_e32 v201, v201
	v_add_f32_e32 v198, 1.0, v198
	v_add_f32_e32 v199, 1.0, v199
	v_add_f32_e32 v200, 1.0, v200
	v_add_f32_e32 v201, 1.0, v201
	v_rcp_f32_e32 v198, v198
	v_rcp_f32_e32 v199, v199
	v_rcp_f32_e32 v200, v200
	v_rcp_f32_e32 v201, v201
	v_mul_f32_e32 v190, v190, v198
	v_mul_f32_e32 v191, v191, v199
	v_mul_f32_e32 v192, v192, v200
	v_mul_f32_e32 v193, v193, v201
	v_mul_f32_e32 v190, v190, v194
	v_mul_f32_e32 v191, v191, v195
	v_mul_f32_e32 v192, v192, v196
	v_mul_f32_e32 v193, v193, v197
	v_cvt_pk_bf16_f32 v234, v190, v191
	v_cvt_pk_bf16_f32 v235, v192, v193
	v_cmp_gt_i32_e32 vcc, s3, v230
	s_and_b64 vcc, vcc, s[54:55]
	s_nop 0
	v_permlane16_swap_b32_e32 v232, v234
	v_permlane16_swap_b32_e32 v233, v235
	s_and_saveexec_b64 s[0:1], vcc
	global_store_dwordx4 v231, v[232:235], s[12:13] offset:128
	s_mov_b64 exec, s[0:1]
